# FFN-up macro-tile loop: operand sets hold 64-deep k-chunks of half the rows alternately, so half of the rows are requested as whole 128-byte lines (was 64-byte half lines for every row)
# speedup vs baseline: 1.0197x; 1.0197x over previous
.LBB0_2769:
	v_readlane_b32 s2, v246, 26
	s_cmp_eq_u32 s2, 10
	s_cselect_b64 s[8:9], -1, 0
	s_load_dwordx2 s[10:11], s[0:1], 0x108
	v_cndmask_b32_e64 v0, 0, 1, s[8:9]
	s_mov_b32 s2, s83
	v_readfirstlane_b32 s0, v0
	s_or_b32 s0, s58, s0
	s_mul_hi_i32 s1, s0, 0xb00000
	s_mul_i32 s0, s0, 0xb00000
	s_waitcnt lgkmcnt(0)
	s_add_u32 s0, s10, s0
	s_addc_u32 s1, s11, s1
	s_add_u32 s0, s0, 0x7c78100
	s_addc_u32 s1, s1, 0
	s_add_u32 s8, s10, 0x3000000
	s_addc_u32 s9, s11, 0
	s_add_u32 s10, s10, 0x14958100
	s_addc_u32 s11, s11, 0
	s_mov_b32 s14, 0x10000
	v_and_b32_e32 v171, 63, v194
	v_lshrrev_b32_e32 v172, 6, v194
	v_lshrrev_b32_e32 v160, 2, v194
	v_lshlrev_b32_e32 v160, 11, v160
	v_and_b32_e32 v173, 3, v171
	v_bfe_u32 v174, v171, 4, 2
	v_xor_b32_e32 v173, v173, v174
	v_lshl_add_u32 v160, v173, 4, v160
	v_add_u32_e32 v161, 0x20000, v160
	v_and_b32_e32 v175, 31, v171
	v_lshrrev_b32_e32 v176, 5, v171
	v_bfe_u32 v177, v175, 2, 2
	v_xor_b32_e32 v178, v176, v177
	v_xor_b32_e32 v179, 2, v178
	v_lshrrev_b32_e32 v180, 1, v172
	v_and_b32_e32 v181, 1, v172
	v_lshl_add_u32 v182, v180, 6, v175
	v_lshl_add_u32 v183, v181, 6, v175
	v_lshlrev_b32_e32 v182, 6, v182
	v_lshlrev_b32_e32 v183, 6, v183
	v_lshl_add_u32 v154, v178, 4, v182
	v_lshl_add_u32 v155, v179, 4, v182
	v_lshl_add_u32 v156, v178, 4, v183
	v_lshl_add_u32 v157, v179, 4, v183
	v_add_u32_e32 v158, 0x2000, v156
	v_add_u32_e32 v159, 0x2000, v157
	v_lshlrev_b32_e32 v184, 6, v180
	v_lshl_add_u32 v184, v176, 2, v184
	v_mul_u32_u24_e32 v184, 0x1600, v184
	v_lshl_add_u32 v185, v181, 5, v175
	v_lshl_add_u32 v162, v185, 1, v184
	v_add_u32_e32 v163, 0x1600, v162
	v_add_u32_e32 v164, 0x2c00, v162
	v_add_u32_e32 v165, 0x4200, v162
	v_lshrrev_b32_e32 v173, 3, v171
	v_lshl_add_u32 v173, v172, 3, v173
	v_lshlrev_b32_e32 v173, 11, v173
	v_and_b32_e32 v174, 1, v172
	v_lshrrev_b32_e32 v177, 4, v171
	v_lshl_add_u32 v174, v174, 2, v177
	v_and_b32_e32 v177, 7, v171
	v_xor_b32_e32 v174, v174, v177
	v_lshl_add_u32 v249, v174, 4, v173
	v_add_u32_e32 v254, 0x20000, v249
	v_add_u32_e32 v166, 0x10000, v249
	v_add_u32_e32 v167, 0x30000, v249
	v_bfe_u32 v177, v175, 1, 3
	v_or_b32_e32 v174, 0, v176
	v_xor_b32_e32 v174, v174, v177
	v_lshlrev_b32_e32 v174, 4, v174
	v_lshl_add_u32 v173, v180, 5, v175
	v_lshl_add_u32 v168, v173, 7, v174
	v_lshl_add_u32 v173, v181, 5, v175
	v_lshl_add_u32 v238, v173, 7, v174
	v_add_u32_e32 v242, 0x4000, v238
	v_or_b32_e32 v174, 4, v176
	v_xor_b32_e32 v174, v174, v177
	v_lshlrev_b32_e32 v174, 4, v174
	v_lshl_add_u32 v173, v180, 5, v175
	v_lshl_add_u32 v169, v173, 7, v174
	v_lshl_add_u32 v173, v181, 5, v175
	v_lshl_add_u32 v239, v173, 7, v174
	v_add_u32_e32 v243, 0x4000, v239
	v_or_b32_e32 v174, 2, v176
	v_xor_b32_e32 v174, v174, v177
	v_lshlrev_b32_e32 v174, 4, v174
	v_lshl_add_u32 v173, v180, 5, v175
	v_lshl_add_u32 v236, v173, 7, v174
	v_lshl_add_u32 v173, v181, 5, v175
	v_lshl_add_u32 v240, v173, 7, v174
	v_add_u32_e32 v244, 0x4000, v240
	v_or_b32_e32 v174, 6, v176
	v_xor_b32_e32 v174, v174, v177
	v_lshlrev_b32_e32 v174, 4, v174
	v_lshl_add_u32 v173, v180, 5, v175
	v_lshl_add_u32 v237, v173, 7, v174
	v_lshl_add_u32 v173, v181, 5, v175
	v_lshl_add_u32 v241, v173, 7, v174
	v_add_u32_e32 v245, 0x4000, v241
	v_readfirstlane_b32 s65, v194
	s_nop 0
	s_lshl_b32 s65, s65, 4
	s_add_u32 s65, s65, 16
	v_readlane_b32 s62, v246, 14
	s_mov_b32 s64, 0

.Lhw_ffnup_dloop:
	s_cmp_ge_u32 s2, s64
	s_cbranch_scc1 .Lhw_ffnup_tail
	s_mul_i32 s6, s2, 745
	s_lshr_b32 s6, s6, 16
	s_mul_i32 s14, s6, 88
	s_sub_i32 s14, s2, s14
	v_readlane_b32 s13, v246, 16
	s_lshl_b32 s6, s6, 2
	s_and_b32 s12, s14, 3
	s_add_i32 s6, s6, s12
	s_add_i32 s6, s6, s13
	s_lshl_b32 s6, s6, 7
	s_lshr_b32 s14, s14, 2
	s_lshl_b32 s14, s14, 8
	s_lshl_b32 vcc_lo, s6, 11
	s_add_u32 s66, s10, vcc_lo
	s_addc_u32 s67, s11, 0
	s_lshl_b32 vcc_lo, s14, 11
	s_add_u32 s12, s0, vcc_lo
	s_addc_u32 s13, s1, 0
	s_add_u32 s62, s12, 0x40000
	s_addc_u32 s63, s13, 0
	s_barrier
	s_sub_u32 s66, s66, 64
	s_subb_u32 s67, s67, 0
	s_sub_u32 s12, s12, 64
	s_subb_u32 s13, s13, 0
	s_sub_u32 s62, s62, 64
	s_subb_u32 s63, s63, 0
	s_add_u32 m0, s65, 0x0
	s_nop 0
	global_load_lds_dwordx4 v166, s[66:67]
	s_add_u32 m0, s65, 0x1000
	s_nop 0
	global_load_lds_dwordx4 v167, s[66:67]
	s_add_u32 m0, s65, 0x2000
	s_nop 0
	global_load_lds_dwordx4 v166, s[12:13]
	s_add_u32 m0, s65, 0x3000
	s_nop 0
	global_load_lds_dwordx4 v167, s[12:13]
	s_add_u32 m0, s65, 0x4000
	s_nop 0
	global_load_lds_dwordx4 v166, s[62:63]
	s_add_u32 m0, s65, 0x5000
	s_nop 0
	global_load_lds_dwordx4 v167, s[62:63]
	s_add_u32 s66, s66, 64
	s_addc_u32 s67, s67, 0
	s_add_u32 s12, s12, 64
	s_addc_u32 s13, s13, 0
	s_add_u32 s62, s62, 64
	s_addc_u32 s63, s63, 0
	s_add_u32 m0, s65, 0x6000
	s_nop 0
	global_load_lds_dwordx4 v249, s[66:67]
	s_add_u32 m0, s65, 0x7000
	s_nop 0
	global_load_lds_dwordx4 v254, s[66:67]
	s_add_u32 m0, s65, 0x8000
	s_nop 0
	global_load_lds_dwordx4 v249, s[12:13]
	s_add_u32 m0, s65, 0x9000
	s_nop 0
	global_load_lds_dwordx4 v254, s[12:13]
	s_add_u32 m0, s65, 0xa000
	s_nop 0
	global_load_lds_dwordx4 v249, s[62:63]
	s_add_u32 m0, s65, 0xb000
	s_nop 0
	global_load_lds_dwordx4 v254, s[62:63]
	s_add_u32 s66, s66, 64
	s_addc_u32 s67, s67, 0
	s_add_u32 s12, s12, 64
	s_addc_u32 s13, s13, 0
	s_add_u32 s62, s62, 64
	s_addc_u32 s63, s63, 0
	v_mov_b32_e32 v2, 0
	v_mov_b32_e32 v3, 0
	v_mov_b32_e32 v4, 0
	v_mov_b32_e32 v5, 0
	v_mov_b32_e32 v6, 0
	v_mov_b32_e32 v7, 0
	v_mov_b32_e32 v8, 0
	v_mov_b32_e32 v9, 0
	v_mov_b32_e32 v10, 0
	v_mov_b32_e32 v11, 0
	v_mov_b32_e32 v12, 0
	v_mov_b32_e32 v13, 0
	v_mov_b32_e32 v14, 0
	v_mov_b32_e32 v15, 0
	v_mov_b32_e32 v16, 0
	v_mov_b32_e32 v17, 0
	v_mov_b32_e32 v18, 0
	v_mov_b32_e32 v19, 0
	v_mov_b32_e32 v20, 0
	v_mov_b32_e32 v21, 0
	v_mov_b32_e32 v22, 0
	v_mov_b32_e32 v23, 0
	v_mov_b32_e32 v24, 0
	v_mov_b32_e32 v25, 0
	v_mov_b32_e32 v26, 0
	v_mov_b32_e32 v27, 0
	v_mov_b32_e32 v28, 0
	v_mov_b32_e32 v29, 0
	v_mov_b32_e32 v30, 0
	v_mov_b32_e32 v31, 0
	v_mov_b32_e32 v32, 0
	v_mov_b32_e32 v33, 0
	v_mov_b32_e32 v34, 0
	v_mov_b32_e32 v35, 0
	v_mov_b32_e32 v36, 0
	v_mov_b32_e32 v37, 0
	v_mov_b32_e32 v38, 0
	v_mov_b32_e32 v39, 0
	v_mov_b32_e32 v40, 0
	v_mov_b32_e32 v41, 0
	v_mov_b32_e32 v42, 0
	v_mov_b32_e32 v43, 0
	v_mov_b32_e32 v44, 0
	v_mov_b32_e32 v45, 0
	v_mov_b32_e32 v46, 0
	v_mov_b32_e32 v47, 0
	v_mov_b32_e32 v48, 0
	v_mov_b32_e32 v49, 0
	v_mov_b32_e32 v50, 0
	v_mov_b32_e32 v51, 0
	v_mov_b32_e32 v52, 0
	v_mov_b32_e32 v53, 0
	v_mov_b32_e32 v54, 0
	v_mov_b32_e32 v55, 0
	v_mov_b32_e32 v56, 0
	v_mov_b32_e32 v57, 0
	v_mov_b32_e32 v58, 0
	v_mov_b32_e32 v59, 0
	v_mov_b32_e32 v60, 0
	v_mov_b32_e32 v61, 0
	v_mov_b32_e32 v62, 0
	v_mov_b32_e32 v63, 0
	v_mov_b32_e32 v64, 0
	v_mov_b32_e32 v65, 0
	v_mov_b32_e32 v66, 0
	v_mov_b32_e32 v67, 0
	v_mov_b32_e32 v68, 0
	v_mov_b32_e32 v69, 0
	v_mov_b32_e32 v70, 0
	v_mov_b32_e32 v71, 0
	v_mov_b32_e32 v72, 0
	v_mov_b32_e32 v73, 0
	v_mov_b32_e32 v74, 0
	v_mov_b32_e32 v75, 0
	v_mov_b32_e32 v76, 0
	v_mov_b32_e32 v77, 0
	v_mov_b32_e32 v78, 0
	v_mov_b32_e32 v79, 0
	v_mov_b32_e32 v80, 0
	v_mov_b32_e32 v81, 0
	v_mov_b32_e32 v82, 0
	v_mov_b32_e32 v83, 0
	v_mov_b32_e32 v84, 0
	v_mov_b32_e32 v85, 0
	v_mov_b32_e32 v86, 0
	v_mov_b32_e32 v87, 0
	v_mov_b32_e32 v88, 0
	v_mov_b32_e32 v89, 0
	v_mov_b32_e32 v90, 0
	v_mov_b32_e32 v91, 0
	v_mov_b32_e32 v92, 0
	v_mov_b32_e32 v93, 0
	v_mov_b32_e32 v94, 0
	v_mov_b32_e32 v95, 0
	v_mov_b32_e32 v96, 0
	v_mov_b32_e32 v97, 0
	v_mov_b32_e32 v98, 0
	v_mov_b32_e32 v99, 0
	v_mov_b32_e32 v100, 0
	v_mov_b32_e32 v101, 0
	v_mov_b32_e32 v102, 0
	v_mov_b32_e32 v103, 0
	v_mov_b32_e32 v104, 0
	v_mov_b32_e32 v105, 0
	v_mov_b32_e32 v106, 0
	v_mov_b32_e32 v107, 0
	v_mov_b32_e32 v108, 0
	v_mov_b32_e32 v109, 0
	v_mov_b32_e32 v110, 0
	v_mov_b32_e32 v111, 0
	v_mov_b32_e32 v112, 0
	v_mov_b32_e32 v113, 0
	v_mov_b32_e32 v114, 0
	v_mov_b32_e32 v115, 0
	v_mov_b32_e32 v116, 0
	v_mov_b32_e32 v117, 0
	v_mov_b32_e32 v118, 0
	v_mov_b32_e32 v119, 0
	v_mov_b32_e32 v120, 0
	v_mov_b32_e32 v121, 0
	v_mov_b32_e32 v122, 0
	v_mov_b32_e32 v123, 0
	v_mov_b32_e32 v124, 0
	v_mov_b32_e32 v125, 0
	v_mov_b32_e32 v126, 0
	v_mov_b32_e32 v127, 0
	v_mov_b32_e32 v128, 0
	v_mov_b32_e32 v129, 0
	s_waitcnt vmcnt(0)
	s_barrier
	ds_read_b128 v[134:137], v169 offset:16
	ds_read_b128 v[142:145], v239 offset:8208
	ds_read_b128 v[150:153], v243 offset:16
	s_mov_b32 s59, 5
.Lhw_ffnup_d_loop:
	s_waitcnt vmcnt(0)
	s_barrier
	ds_read_b128 v[130:133], v168 offset:24592
	ds_read_b128 v[138:141], v238 offset:32784
	ds_read_b128 v[146:149], v242 offset:24592
	s_waitcnt lgkmcnt(4)
	v_mfma_f32_32x32x16_bf16 v[50:65], v[134:137], v[142:145], v[50:65]
	s_add_u32 m0, s65, 0xc000
	ds_read_b128 v[216:219], v237 offset:16
	global_load_lds_dwordx4 v166, s[66:67]
	s_waitcnt lgkmcnt(4)
	v_mfma_f32_32x32x16_bf16 v[114:129], v[134:137], v[150:153], v[114:129]
	s_add_u32 m0, s65, 0xd000
	ds_read_b128 v[224:227], v241 offset:8208
	global_load_lds_dwordx4 v167, s[66:67]
	s_waitcnt lgkmcnt(4)
	v_mfma_f32_32x32x16_bf16 v[18:33], v[130:133], v[142:145], v[18:33]
	s_add_u32 m0, s65, 0xe000
	ds_read_b128 v[232:235], v245 offset:16
	global_load_lds_dwordx4 v166, s[12:13]
	s_waitcnt lgkmcnt(4)
	v_mfma_f32_32x32x16_bf16 v[34:49], v[134:137], v[138:141], v[34:49]
	s_add_u32 m0, s65, 0xf000
	ds_read_b128 v[212:215], v236 offset:24592
	global_load_lds_dwordx4 v167, s[12:13]
	v_mfma_f32_32x32x16_bf16 v[82:97], v[130:133], v[150:153], v[82:97]
	s_add_u32 m0, s65, 0x10000
	ds_read_b128 v[220:223], v240 offset:32784
	global_load_lds_dwordx4 v166, s[62:63]
	s_waitcnt lgkmcnt(5)
	v_mfma_f32_32x32x16_bf16 v[98:113], v[134:137], v[146:149], v[98:113]
	s_add_u32 m0, s65, 0x11000
	ds_read_b128 v[228:231], v244 offset:24592
	global_load_lds_dwordx4 v167, s[62:63]
	v_mfma_f32_32x32x16_bf16 v[2:17], v[130:133], v[138:141], v[2:17]
	v_mfma_f32_32x32x16_bf16 v[66:81], v[130:133], v[146:149], v[66:81]
	s_waitcnt lgkmcnt(4)
	v_mfma_f32_32x32x16_bf16 v[50:65], v[216:219], v[224:227], v[50:65]
	ds_read_b128 v[130:133], v169 offset:24592
	s_waitcnt lgkmcnt(4)
	v_mfma_f32_32x32x16_bf16 v[114:129], v[216:219], v[232:235], v[114:129]
	ds_read_b128 v[138:141], v239 offset:32784
	s_waitcnt lgkmcnt(4)
	v_mfma_f32_32x32x16_bf16 v[18:33], v[212:215], v[224:227], v[18:33]
	ds_read_b128 v[146:149], v243 offset:24592
	s_waitcnt lgkmcnt(4)
	v_mfma_f32_32x32x16_bf16 v[34:49], v[216:219], v[220:223], v[34:49]
	s_add_u32 s66, s66, 64
	s_addc_u32 s67, s67, 0
	v_mfma_f32_32x32x16_bf16 v[82:97], v[212:215], v[232:235], v[82:97]
	s_add_u32 s12, s12, 64
	s_addc_u32 s13, s13, 0
	s_waitcnt lgkmcnt(3)
	v_mfma_f32_32x32x16_bf16 v[98:113], v[216:219], v[228:231], v[98:113]
	s_add_u32 s62, s62, 64
	s_addc_u32 s63, s63, 0
	v_mfma_f32_32x32x16_bf16 v[2:17], v[212:215], v[220:223], v[2:17]
	v_mfma_f32_32x32x16_bf16 v[66:81], v[212:215], v[228:231], v[66:81]
	s_waitcnt vmcnt(0)
	s_barrier
	ds_read_b128 v[134:137], v168 offset:49168
	ds_read_b128 v[142:145], v238 offset:57360
	ds_read_b128 v[150:153], v242 offset:49168
	s_waitcnt lgkmcnt(4)
	v_mfma_f32_32x32x16_bf16 v[2:17], v[130:133], v[138:141], v[2:17]
	s_add_u32 m0, s65, 0x0
	ds_read_b128 v[212:215], v237 offset:24592
	global_load_lds_dwordx4 v249, s[66:67]
	s_waitcnt lgkmcnt(4)
	v_mfma_f32_32x32x16_bf16 v[66:81], v[130:133], v[146:149], v[66:81]
	s_add_u32 m0, s65, 0x1000
	ds_read_b128 v[220:223], v241 offset:32784
	global_load_lds_dwordx4 v254, s[66:67]
	s_waitcnt lgkmcnt(3)
	v_mfma_f32_32x32x16_bf16 v[18:33], v[130:133], v[142:145], v[18:33]
	s_add_u32 m0, s65, 0x2000
	ds_read_b128 v[228:231], v245 offset:24592
	global_load_lds_dwordx4 v249, s[12:13]
	v_mfma_f32_32x32x16_bf16 v[34:49], v[134:137], v[138:141], v[34:49]
	s_add_u32 m0, s65, 0x3000
	ds_read_b128 v[216:219], v236 offset:49168
	global_load_lds_dwordx4 v254, s[12:13]
	s_waitcnt lgkmcnt(4)
	v_mfma_f32_32x32x16_bf16 v[82:97], v[130:133], v[150:153], v[82:97]
	s_add_u32 m0, s65, 0x4000
	ds_read_b128 v[224:227], v240 offset:57360
	global_load_lds_dwordx4 v249, s[62:63]
	v_mfma_f32_32x32x16_bf16 v[98:113], v[134:137], v[146:149], v[98:113]
	s_add_u32 m0, s65, 0x5000
	ds_read_b128 v[232:235], v244 offset:49168
	global_load_lds_dwordx4 v254, s[62:63]
	v_mfma_f32_32x32x16_bf16 v[50:65], v[134:137], v[142:145], v[50:65]
	v_mfma_f32_32x32x16_bf16 v[114:129], v[134:137], v[150:153], v[114:129]
	s_waitcnt lgkmcnt(4)
	v_mfma_f32_32x32x16_bf16 v[2:17], v[212:215], v[220:223], v[2:17]
	ds_read_b128 v[134:137], v169 offset:49168
	s_waitcnt lgkmcnt(4)
	v_mfma_f32_32x32x16_bf16 v[66:81], v[212:215], v[228:231], v[66:81]
	ds_read_b128 v[142:145], v239 offset:57360
	s_waitcnt lgkmcnt(3)
	v_mfma_f32_32x32x16_bf16 v[18:33], v[212:215], v[224:227], v[18:33]
	ds_read_b128 v[150:153], v243 offset:49168
	v_mfma_f32_32x32x16_bf16 v[34:49], v[216:219], v[220:223], v[34:49]
	s_add_u32 s66, s66, 64
	s_addc_u32 s67, s67, 0
	s_waitcnt lgkmcnt(3)
	v_mfma_f32_32x32x16_bf16 v[82:97], v[212:215], v[232:235], v[82:97]
	s_add_u32 s12, s12, 64
	s_addc_u32 s13, s13, 0
	v_mfma_f32_32x32x16_bf16 v[98:113], v[216:219], v[228:231], v[98:113]
	s_add_u32 s62, s62, 64
	s_addc_u32 s63, s63, 0
	v_mfma_f32_32x32x16_bf16 v[50:65], v[216:219], v[224:227], v[50:65]
	v_mfma_f32_32x32x16_bf16 v[114:129], v[216:219], v[232:235], v[114:129]
	s_waitcnt vmcnt(0)
	s_barrier
	ds_read_b128 v[130:133], v168 offset:16
	ds_read_b128 v[138:141], v238 offset:8208
	ds_read_b128 v[146:149], v242 offset:16
	s_waitcnt lgkmcnt(4)
	v_mfma_f32_32x32x16_bf16 v[50:65], v[134:137], v[142:145], v[50:65]
	s_add_u32 m0, s65, 0x6000
	ds_read_b128 v[216:219], v237 offset:49168
	global_load_lds_dwordx4 v166, s[66:67]
	s_waitcnt lgkmcnt(4)
	v_mfma_f32_32x32x16_bf16 v[114:129], v[134:137], v[150:153], v[114:129]
	s_add_u32 m0, s65, 0x7000
	ds_read_b128 v[224:227], v241 offset:57360
	global_load_lds_dwordx4 v167, s[66:67]
	s_waitcnt lgkmcnt(4)
	v_mfma_f32_32x32x16_bf16 v[18:33], v[130:133], v[142:145], v[18:33]
	s_add_u32 m0, s65, 0x8000
	ds_read_b128 v[232:235], v245 offset:49168
	global_load_lds_dwordx4 v166, s[12:13]
	s_waitcnt lgkmcnt(4)
	v_mfma_f32_32x32x16_bf16 v[34:49], v[134:137], v[138:141], v[34:49]
	s_add_u32 m0, s65, 0x9000
	ds_read_b128 v[212:215], v236 offset:16
	global_load_lds_dwordx4 v167, s[12:13]
	v_mfma_f32_32x32x16_bf16 v[82:97], v[130:133], v[150:153], v[82:97]
	s_add_u32 m0, s65, 0xa000
	ds_read_b128 v[220:223], v240 offset:8208
	global_load_lds_dwordx4 v166, s[62:63]
	s_waitcnt lgkmcnt(5)
	v_mfma_f32_32x32x16_bf16 v[98:113], v[134:137], v[146:149], v[98:113]
	s_add_u32 m0, s65, 0xb000
	ds_read_b128 v[228:231], v244 offset:16
	global_load_lds_dwordx4 v167, s[62:63]
	v_mfma_f32_32x32x16_bf16 v[2:17], v[130:133], v[138:141], v[2:17]
	v_mfma_f32_32x32x16_bf16 v[66:81], v[130:133], v[146:149], v[66:81]
	s_waitcnt lgkmcnt(4)
	v_mfma_f32_32x32x16_bf16 v[50:65], v[216:219], v[224:227], v[50:65]
	ds_read_b128 v[130:133], v169 offset:16
	s_waitcnt lgkmcnt(4)
	v_mfma_f32_32x32x16_bf16 v[114:129], v[216:219], v[232:235], v[114:129]
	ds_read_b128 v[138:141], v239 offset:8208
	s_waitcnt lgkmcnt(4)
	v_mfma_f32_32x32x16_bf16 v[18:33], v[212:215], v[224:227], v[18:33]
	ds_read_b128 v[146:149], v243 offset:16
	s_waitcnt lgkmcnt(4)
	v_mfma_f32_32x32x16_bf16 v[34:49], v[216:219], v[220:223], v[34:49]
	s_add_u32 s66, s66, 64
	s_addc_u32 s67, s67, 0
	v_mfma_f32_32x32x16_bf16 v[82:97], v[212:215], v[232:235], v[82:97]
	s_add_u32 s12, s12, 64
	s_addc_u32 s13, s13, 0
	s_waitcnt lgkmcnt(3)
	v_mfma_f32_32x32x16_bf16 v[98:113], v[216:219], v[228:231], v[98:113]
	s_add_u32 s62, s62, 64
	s_addc_u32 s63, s63, 0
	v_mfma_f32_32x32x16_bf16 v[2:17], v[212:215], v[220:223], v[2:17]
	v_mfma_f32_32x32x16_bf16 v[66:81], v[212:215], v[228:231], v[66:81]
	s_waitcnt vmcnt(0)
	s_barrier
	ds_read_b128 v[134:137], v168 offset:24592
	ds_read_b128 v[142:145], v238 offset:32784
	ds_read_b128 v[150:153], v242 offset:24592
	s_waitcnt lgkmcnt(4)
	v_mfma_f32_32x32x16_bf16 v[2:17], v[130:133], v[138:141], v[2:17]
	s_add_u32 m0, s65, 0xc000
	ds_read_b128 v[212:215], v237 offset:16
	global_load_lds_dwordx4 v249, s[66:67]
	s_waitcnt lgkmcnt(4)
	v_mfma_f32_32x32x16_bf16 v[66:81], v[130:133], v[146:149], v[66:81]
	s_add_u32 m0, s65, 0xd000
	ds_read_b128 v[220:223], v241 offset:8208
	global_load_lds_dwordx4 v254, s[66:67]
	s_waitcnt lgkmcnt(3)
	v_mfma_f32_32x32x16_bf16 v[18:33], v[130:133], v[142:145], v[18:33]
	s_add_u32 m0, s65, 0xe000
	ds_read_b128 v[228:231], v245 offset:16
	global_load_lds_dwordx4 v249, s[12:13]
	v_mfma_f32_32x32x16_bf16 v[34:49], v[134:137], v[138:141], v[34:49]
	s_add_u32 m0, s65, 0xf000
	ds_read_b128 v[216:219], v236 offset:24592
	global_load_lds_dwordx4 v254, s[12:13]
	s_waitcnt lgkmcnt(4)
	v_mfma_f32_32x32x16_bf16 v[82:97], v[130:133], v[150:153], v[82:97]
	s_add_u32 m0, s65, 0x10000
	ds_read_b128 v[224:227], v240 offset:32784
	global_load_lds_dwordx4 v249, s[62:63]
	v_mfma_f32_32x32x16_bf16 v[98:113], v[134:137], v[146:149], v[98:113]
	s_add_u32 m0, s65, 0x11000
	ds_read_b128 v[232:235], v244 offset:24592
	global_load_lds_dwordx4 v254, s[62:63]
	v_mfma_f32_32x32x16_bf16 v[50:65], v[134:137], v[142:145], v[50:65]
	v_mfma_f32_32x32x16_bf16 v[114:129], v[134:137], v[150:153], v[114:129]
	s_waitcnt lgkmcnt(4)
	v_mfma_f32_32x32x16_bf16 v[2:17], v[212:215], v[220:223], v[2:17]
	ds_read_b128 v[134:137], v169 offset:24592
	s_waitcnt lgkmcnt(4)
	v_mfma_f32_32x32x16_bf16 v[66:81], v[212:215], v[228:231], v[66:81]
	ds_read_b128 v[142:145], v239 offset:32784
	s_waitcnt lgkmcnt(3)
	v_mfma_f32_32x32x16_bf16 v[18:33], v[212:215], v[224:227], v[18:33]
	ds_read_b128 v[150:153], v243 offset:24592
	v_mfma_f32_32x32x16_bf16 v[34:49], v[216:219], v[220:223], v[34:49]
	s_add_u32 s66, s66, 64
	s_addc_u32 s67, s67, 0
	s_waitcnt lgkmcnt(3)
	v_mfma_f32_32x32x16_bf16 v[82:97], v[212:215], v[232:235], v[82:97]
	s_add_u32 s12, s12, 64
	s_addc_u32 s13, s13, 0
	v_mfma_f32_32x32x16_bf16 v[98:113], v[216:219], v[228:231], v[98:113]
	s_add_u32 s62, s62, 64
	s_addc_u32 s63, s63, 0
	v_mfma_f32_32x32x16_bf16 v[50:65], v[216:219], v[224:227], v[50:65]
	v_mfma_f32_32x32x16_bf16 v[114:129], v[216:219], v[232:235], v[114:129]
	s_waitcnt vmcnt(0)
	s_barrier
	ds_read_b128 v[130:133], v168 offset:49168
	ds_read_b128 v[138:141], v238 offset:57360
	ds_read_b128 v[146:149], v242 offset:49168
	s_waitcnt lgkmcnt(4)
	v_mfma_f32_32x32x16_bf16 v[50:65], v[134:137], v[142:145], v[50:65]
	s_add_u32 m0, s65, 0x0
	ds_read_b128 v[216:219], v237 offset:24592
	global_load_lds_dwordx4 v166, s[66:67]
	s_waitcnt lgkmcnt(4)
	v_mfma_f32_32x32x16_bf16 v[114:129], v[134:137], v[150:153], v[114:129]
	s_add_u32 m0, s65, 0x1000
	ds_read_b128 v[224:227], v241 offset:32784
	global_load_lds_dwordx4 v167, s[66:67]
	s_waitcnt lgkmcnt(4)
	v_mfma_f32_32x32x16_bf16 v[18:33], v[130:133], v[142:145], v[18:33]
	s_add_u32 m0, s65, 0x2000
	ds_read_b128 v[232:235], v245 offset:24592
	global_load_lds_dwordx4 v166, s[12:13]
	s_waitcnt lgkmcnt(4)
	v_mfma_f32_32x32x16_bf16 v[34:49], v[134:137], v[138:141], v[34:49]
	s_add_u32 m0, s65, 0x3000
	ds_read_b128 v[212:215], v236 offset:49168
	global_load_lds_dwordx4 v167, s[12:13]
	v_mfma_f32_32x32x16_bf16 v[82:97], v[130:133], v[150:153], v[82:97]
	s_add_u32 m0, s65, 0x4000
	ds_read_b128 v[220:223], v240 offset:57360
	global_load_lds_dwordx4 v166, s[62:63]
	s_waitcnt lgkmcnt(5)
	v_mfma_f32_32x32x16_bf16 v[98:113], v[134:137], v[146:149], v[98:113]
	s_add_u32 m0, s65, 0x5000
	ds_read_b128 v[228:231], v244 offset:49168
	global_load_lds_dwordx4 v167, s[62:63]
	v_mfma_f32_32x32x16_bf16 v[2:17], v[130:133], v[138:141], v[2:17]
	v_mfma_f32_32x32x16_bf16 v[66:81], v[130:133], v[146:149], v[66:81]
	s_waitcnt lgkmcnt(4)
	v_mfma_f32_32x32x16_bf16 v[50:65], v[216:219], v[224:227], v[50:65]
	ds_read_b128 v[130:133], v169 offset:49168
	s_waitcnt lgkmcnt(4)
	v_mfma_f32_32x32x16_bf16 v[114:129], v[216:219], v[232:235], v[114:129]
	ds_read_b128 v[138:141], v239 offset:57360
	s_waitcnt lgkmcnt(4)
	v_mfma_f32_32x32x16_bf16 v[18:33], v[212:215], v[224:227], v[18:33]
	ds_read_b128 v[146:149], v243 offset:49168
	s_waitcnt lgkmcnt(4)
	v_mfma_f32_32x32x16_bf16 v[34:49], v[216:219], v[220:223], v[34:49]
	s_add_u32 s66, s66, 64
	s_addc_u32 s67, s67, 0
	v_mfma_f32_32x32x16_bf16 v[82:97], v[212:215], v[232:235], v[82:97]
	s_add_u32 s12, s12, 64
	s_addc_u32 s13, s13, 0
	s_waitcnt lgkmcnt(3)
	v_mfma_f32_32x32x16_bf16 v[98:113], v[216:219], v[228:231], v[98:113]
	s_add_u32 s62, s62, 64
	s_addc_u32 s63, s63, 0
	v_mfma_f32_32x32x16_bf16 v[2:17], v[212:215], v[220:223], v[2:17]
	v_mfma_f32_32x32x16_bf16 v[66:81], v[212:215], v[228:231], v[66:81]
	s_waitcnt vmcnt(0)
	s_barrier
	ds_read_b128 v[134:137], v168 offset:16
	ds_read_b128 v[142:145], v238 offset:8208
	ds_read_b128 v[150:153], v242 offset:16
	s_waitcnt lgkmcnt(4)
	v_mfma_f32_32x32x16_bf16 v[2:17], v[130:133], v[138:141], v[2:17]
	s_add_u32 m0, s65, 0x6000
	ds_read_b128 v[212:215], v237 offset:49168
	global_load_lds_dwordx4 v249, s[66:67]
	s_waitcnt lgkmcnt(4)
	v_mfma_f32_32x32x16_bf16 v[66:81], v[130:133], v[146:149], v[66:81]
	s_add_u32 m0, s65, 0x7000
	ds_read_b128 v[220:223], v241 offset:57360
	global_load_lds_dwordx4 v254, s[66:67]
	s_waitcnt lgkmcnt(3)
	v_mfma_f32_32x32x16_bf16 v[18:33], v[130:133], v[142:145], v[18:33]
	s_add_u32 m0, s65, 0x8000
	ds_read_b128 v[228:231], v245 offset:49168
	global_load_lds_dwordx4 v249, s[12:13]
	v_mfma_f32_32x32x16_bf16 v[34:49], v[134:137], v[138:141], v[34:49]
	s_add_u32 m0, s65, 0x9000
	ds_read_b128 v[216:219], v236 offset:16
	global_load_lds_dwordx4 v254, s[12:13]
	s_waitcnt lgkmcnt(4)
	v_mfma_f32_32x32x16_bf16 v[82:97], v[130:133], v[150:153], v[82:97]
	s_add_u32 m0, s65, 0xa000
	ds_read_b128 v[224:227], v240 offset:8208
	global_load_lds_dwordx4 v249, s[62:63]
	v_mfma_f32_32x32x16_bf16 v[98:113], v[134:137], v[146:149], v[98:113]
	s_add_u32 m0, s65, 0xb000
	ds_read_b128 v[232:235], v244 offset:16
	global_load_lds_dwordx4 v254, s[62:63]
	v_mfma_f32_32x32x16_bf16 v[50:65], v[134:137], v[142:145], v[50:65]
	v_mfma_f32_32x32x16_bf16 v[114:129], v[134:137], v[150:153], v[114:129]
	s_waitcnt lgkmcnt(4)
	v_mfma_f32_32x32x16_bf16 v[2:17], v[212:215], v[220:223], v[2:17]
	ds_read_b128 v[134:137], v169 offset:16
	s_waitcnt lgkmcnt(4)
	v_mfma_f32_32x32x16_bf16 v[66:81], v[212:215], v[228:231], v[66:81]
	ds_read_b128 v[142:145], v239 offset:8208
	s_waitcnt lgkmcnt(3)
	v_mfma_f32_32x32x16_bf16 v[18:33], v[212:215], v[224:227], v[18:33]
	ds_read_b128 v[150:153], v243 offset:16
	v_mfma_f32_32x32x16_bf16 v[34:49], v[216:219], v[220:223], v[34:49]
	s_add_u32 s66, s66, 64
	s_addc_u32 s67, s67, 0
	s_waitcnt lgkmcnt(3)
	v_mfma_f32_32x32x16_bf16 v[82:97], v[212:215], v[232:235], v[82:97]
	s_add_u32 s12, s12, 64
	s_addc_u32 s13, s13, 0
	v_mfma_f32_32x32x16_bf16 v[98:113], v[216:219], v[228:231], v[98:113]
	s_add_u32 s62, s62, 64
	s_addc_u32 s63, s63, 0
	v_mfma_f32_32x32x16_bf16 v[50:65], v[216:219], v[224:227], v[50:65]
	v_mfma_f32_32x32x16_bf16 v[114:129], v[216:219], v[232:235], v[114:129]
	s_sub_u32 s59, s59, 1
	s_cmp_lg_u32 s59, 0
	s_cbranch_scc1 .Lhw_ffnup_d_loop
	s_waitcnt vmcnt(0)
	s_barrier
	ds_read_b128 v[130:133], v168 offset:24592
	ds_read_b128 v[138:141], v238 offset:32784
	ds_read_b128 v[146:149], v242 offset:24592
	s_waitcnt lgkmcnt(4)
	v_mfma_f32_32x32x16_bf16 v[50:65], v[134:137], v[142:145], v[50:65]
	s_add_u32 m0, s65, 0xc000
	ds_read_b128 v[216:219], v237 offset:16
	global_load_lds_dwordx4 v166, s[66:67]
	s_waitcnt lgkmcnt(4)
	v_mfma_f32_32x32x16_bf16 v[114:129], v[134:137], v[150:153], v[114:129]
	s_add_u32 m0, s65, 0xd000
	ds_read_b128 v[224:227], v241 offset:8208
	global_load_lds_dwordx4 v167, s[66:67]
	s_waitcnt lgkmcnt(4)
	v_mfma_f32_32x32x16_bf16 v[18:33], v[130:133], v[142:145], v[18:33]
	s_add_u32 m0, s65, 0xe000
	ds_read_b128 v[232:235], v245 offset:16
	global_load_lds_dwordx4 v166, s[12:13]
	s_waitcnt lgkmcnt(4)
	v_mfma_f32_32x32x16_bf16 v[34:49], v[134:137], v[138:141], v[34:49]
	s_add_u32 m0, s65, 0xf000
	ds_read_b128 v[212:215], v236 offset:24592
	global_load_lds_dwordx4 v167, s[12:13]
	v_mfma_f32_32x32x16_bf16 v[82:97], v[130:133], v[150:153], v[82:97]
	s_add_u32 m0, s65, 0x10000
	ds_read_b128 v[220:223], v240 offset:32784
	global_load_lds_dwordx4 v166, s[62:63]
	s_waitcnt lgkmcnt(5)
	v_mfma_f32_32x32x16_bf16 v[98:113], v[134:137], v[146:149], v[98:113]
	s_add_u32 m0, s65, 0x11000
	ds_read_b128 v[228:231], v244 offset:24592
	global_load_lds_dwordx4 v167, s[62:63]
	v_mfma_f32_32x32x16_bf16 v[2:17], v[130:133], v[138:141], v[2:17]
	v_mfma_f32_32x32x16_bf16 v[66:81], v[130:133], v[146:149], v[66:81]
	s_waitcnt lgkmcnt(4)
	v_mfma_f32_32x32x16_bf16 v[50:65], v[216:219], v[224:227], v[50:65]
	ds_read_b128 v[130:133], v169 offset:24592
	s_waitcnt lgkmcnt(4)
	v_mfma_f32_32x32x16_bf16 v[114:129], v[216:219], v[232:235], v[114:129]
	ds_read_b128 v[138:141], v239 offset:32784
	s_waitcnt lgkmcnt(4)
	v_mfma_f32_32x32x16_bf16 v[18:33], v[212:215], v[224:227], v[18:33]
	ds_read_b128 v[146:149], v243 offset:24592
	s_waitcnt lgkmcnt(4)
	v_mfma_f32_32x32x16_bf16 v[34:49], v[216:219], v[220:223], v[34:49]
	s_add_u32 s66, s66, 64
	s_addc_u32 s67, s67, 0
	v_mfma_f32_32x32x16_bf16 v[82:97], v[212:215], v[232:235], v[82:97]
	s_add_u32 s12, s12, 64
	s_addc_u32 s13, s13, 0
	s_waitcnt lgkmcnt(3)
	v_mfma_f32_32x32x16_bf16 v[98:113], v[216:219], v[228:231], v[98:113]
	s_add_u32 s62, s62, 64
	s_addc_u32 s63, s63, 0
	v_mfma_f32_32x32x16_bf16 v[2:17], v[212:215], v[220:223], v[2:17]
	v_mfma_f32_32x32x16_bf16 v[66:81], v[212:215], v[228:231], v[66:81]
	s_waitcnt vmcnt(0)
	s_barrier
	ds_read_b128 v[134:137], v168 offset:49168
	ds_read_b128 v[142:145], v238 offset:57360
	ds_read_b128 v[150:153], v242 offset:49168
	s_waitcnt lgkmcnt(4)
	v_mfma_f32_32x32x16_bf16 v[2:17], v[130:133], v[138:141], v[2:17]
	ds_read_b128 v[212:215], v237 offset:24592
	s_waitcnt lgkmcnt(4)
	v_mfma_f32_32x32x16_bf16 v[66:81], v[130:133], v[146:149], v[66:81]
	ds_read_b128 v[220:223], v241 offset:32784
	s_waitcnt lgkmcnt(3)
	v_mfma_f32_32x32x16_bf16 v[18:33], v[130:133], v[142:145], v[18:33]
	ds_read_b128 v[228:231], v245 offset:24592
	v_mfma_f32_32x32x16_bf16 v[34:49], v[134:137], v[138:141], v[34:49]
	ds_read_b128 v[216:219], v236 offset:49168
	s_waitcnt lgkmcnt(4)
	v_mfma_f32_32x32x16_bf16 v[82:97], v[130:133], v[150:153], v[82:97]
	ds_read_b128 v[224:227], v240 offset:57360
	v_mfma_f32_32x32x16_bf16 v[98:113], v[134:137], v[146:149], v[98:113]
	ds_read_b128 v[232:235], v244 offset:49168
	v_mfma_f32_32x32x16_bf16 v[50:65], v[134:137], v[142:145], v[50:65]
	v_mfma_f32_32x32x16_bf16 v[114:129], v[134:137], v[150:153], v[114:129]
	s_waitcnt lgkmcnt(4)
	v_mfma_f32_32x32x16_bf16 v[2:17], v[212:215], v[220:223], v[2:17]
	s_waitcnt lgkmcnt(3)
	v_mfma_f32_32x32x16_bf16 v[66:81], v[212:215], v[228:231], v[66:81]
	s_waitcnt lgkmcnt(1)
	v_mfma_f32_32x32x16_bf16 v[18:33], v[212:215], v[224:227], v[18:33]
	v_mfma_f32_32x32x16_bf16 v[34:49], v[216:219], v[220:223], v[34:49]
	s_waitcnt lgkmcnt(0)
	v_mfma_f32_32x32x16_bf16 v[82:97], v[212:215], v[232:235], v[82:97]
	v_mfma_f32_32x32x16_bf16 v[98:113], v[216:219], v[228:231], v[98:113]
	v_mfma_f32_32x32x16_bf16 v[50:65], v[216:219], v[224:227], v[50:65]
	v_mfma_f32_32x32x16_bf16 v[114:129], v[216:219], v[232:235], v[114:129]
	s_nop 7
	s_nop 7
	s_mul_i32 vcc_lo, s6, 0x1600
	s_add_u32 s66, s8, vcc_lo
	s_addc_u32 s67, s9, 0
	s_add_u32 s66, s66, s14
	s_addc_u32 s67, s67, 0
	v_mul_f32_e32 v171, 0xbfb8aa3b, v2
	v_mul_f32_e32 v172, 0xbfb8aa3b, v3
	v_mul_f32_e32 v173, 0xbfb8aa3b, v4
	v_mul_f32_e32 v174, 0xbfb8aa3b, v5
	v_exp_f32_e32 v171, v171
	v_exp_f32_e32 v172, v172
	v_exp_f32_e32 v173, v173
	v_exp_f32_e32 v174, v174
	s_nop 0
	v_add_f32_e32 v171, 1.0, v171
	v_add_f32_e32 v172, 1.0, v172
	v_add_f32_e32 v173, 1.0, v173
	v_add_f32_e32 v174, 1.0, v174
	v_rcp_f32_e32 v171, v171
	v_rcp_f32_e32 v172, v172
	v_rcp_f32_e32 v173, v173
	v_rcp_f32_e32 v174, v174
	s_nop 0
	v_mul_f32_e32 v171, v2, v171
	v_mul_f32_e32 v172, v3, v172
	v_mul_f32_e32 v173, v4, v173
	v_mul_f32_e32 v174, v5, v174
	v_mul_f32_e32 v171, v18, v171
	v_mul_f32_e32 v172, v19, v172
	v_mul_f32_e32 v173, v20, v173
	v_mul_f32_e32 v174, v21, v174
	v_cvt_pk_bf16_f32 v179, v171, v171
	v_cvt_pk_bf16_f32 v180, v172, v172
	v_cvt_pk_bf16_f32 v181, v173, v173
	v_cvt_pk_bf16_f32 v182, v174, v174
	global_store_short v162, v179, s[66:67]
	global_store_short v163, v180, s[66:67]
	global_store_short v164, v181, s[66:67]
	global_store_short v165, v182, s[66:67]
	s_add_u32 s66, s66, 0xb000
	s_addc_u32 s67, s67, 0
	v_mul_f32_e32 v171, 0xbfb8aa3b, v6
	v_mul_f32_e32 v172, 0xbfb8aa3b, v7
	v_mul_f32_e32 v173, 0xbfb8aa3b, v8
	v_mul_f32_e32 v174, 0xbfb8aa3b, v9
	v_exp_f32_e32 v171, v171
	v_exp_f32_e32 v172, v172
	v_exp_f32_e32 v173, v173
	v_exp_f32_e32 v174, v174
	s_nop 0
	v_add_f32_e32 v171, 1.0, v171
	v_add_f32_e32 v172, 1.0, v172
	v_add_f32_e32 v173, 1.0, v173
	v_add_f32_e32 v174, 1.0, v174
	v_rcp_f32_e32 v171, v171
	v_rcp_f32_e32 v172, v172
	v_rcp_f32_e32 v173, v173
	v_rcp_f32_e32 v174, v174
	s_nop 0
	v_mul_f32_e32 v171, v6, v171
	v_mul_f32_e32 v172, v7, v172
	v_mul_f32_e32 v173, v8, v173
	v_mul_f32_e32 v174, v9, v174
	v_mul_f32_e32 v171, v22, v171
	v_mul_f32_e32 v172, v23, v172
	v_mul_f32_e32 v173, v24, v173
	v_mul_f32_e32 v174, v25, v174
	v_cvt_pk_bf16_f32 v179, v171, v171
	v_cvt_pk_bf16_f32 v180, v172, v172
	v_cvt_pk_bf16_f32 v181, v173, v173
	v_cvt_pk_bf16_f32 v182, v174, v174
	global_store_short v162, v179, s[66:67]
	global_store_short v163, v180, s[66:67]
	global_store_short v164, v181, s[66:67]
	global_store_short v165, v182, s[66:67]
	s_add_u32 s66, s66, 0xb000
	s_addc_u32 s67, s67, 0
	v_mul_f32_e32 v171, 0xbfb8aa3b, v10
	v_mul_f32_e32 v172, 0xbfb8aa3b, v11
	v_mul_f32_e32 v173, 0xbfb8aa3b, v12
	v_mul_f32_e32 v174, 0xbfb8aa3b, v13
	v_exp_f32_e32 v171, v171
	v_exp_f32_e32 v172, v172
	v_exp_f32_e32 v173, v173
	v_exp_f32_e32 v174, v174
	s_nop 0
	v_add_f32_e32 v171, 1.0, v171
	v_add_f32_e32 v172, 1.0, v172
	v_add_f32_e32 v173, 1.0, v173
	v_add_f32_e32 v174, 1.0, v174
	v_rcp_f32_e32 v171, v171
	v_rcp_f32_e32 v172, v172
	v_rcp_f32_e32 v173, v173
	v_rcp_f32_e32 v174, v174
	s_nop 0
	v_mul_f32_e32 v171, v10, v171
	v_mul_f32_e32 v172, v11, v172
	v_mul_f32_e32 v173, v12, v173
	v_mul_f32_e32 v174, v13, v174
	v_mul_f32_e32 v171, v26, v171
	v_mul_f32_e32 v172, v27, v172
	v_mul_f32_e32 v173, v28, v173
	v_mul_f32_e32 v174, v29, v174
	v_cvt_pk_bf16_f32 v179, v171, v171
	v_cvt_pk_bf16_f32 v180, v172, v172
	v_cvt_pk_bf16_f32 v181, v173, v173
	v_cvt_pk_bf16_f32 v182, v174, v174
	global_store_short v162, v179, s[66:67]
	global_store_short v163, v180, s[66:67]
	global_store_short v164, v181, s[66:67]
	global_store_short v165, v182, s[66:67]
	s_add_u32 s66, s66, 0xb000
	s_addc_u32 s67, s67, 0
	v_mul_f32_e32 v171, 0xbfb8aa3b, v14
	v_mul_f32_e32 v172, 0xbfb8aa3b, v15
	v_mul_f32_e32 v173, 0xbfb8aa3b, v16
	v_mul_f32_e32 v174, 0xbfb8aa3b, v17
	v_exp_f32_e32 v171, v171
	v_exp_f32_e32 v172, v172
	v_exp_f32_e32 v173, v173
	v_exp_f32_e32 v174, v174
	s_nop 0
	v_add_f32_e32 v171, 1.0, v171
	v_add_f32_e32 v172, 1.0, v172
	v_add_f32_e32 v173, 1.0, v173
	v_add_f32_e32 v174, 1.0, v174
	v_rcp_f32_e32 v171, v171
	v_rcp_f32_e32 v172, v172
	v_rcp_f32_e32 v173, v173
	v_rcp_f32_e32 v174, v174
	s_nop 0
	v_mul_f32_e32 v171, v14, v171
	v_mul_f32_e32 v172, v15, v172
	v_mul_f32_e32 v173, v16, v173
	v_mul_f32_e32 v174, v17, v174
	v_mul_f32_e32 v171, v30, v171
	v_mul_f32_e32 v172, v31, v172
	v_mul_f32_e32 v173, v32, v173
	v_mul_f32_e32 v174, v33, v174
	v_cvt_pk_bf16_f32 v179, v171, v171
	v_cvt_pk_bf16_f32 v180, v172, v172
	v_cvt_pk_bf16_f32 v181, v173, v173
	v_cvt_pk_bf16_f32 v182, v174, v174
	global_store_short v162, v179, s[66:67]
	global_store_short v163, v180, s[66:67]
	global_store_short v164, v181, s[66:67]
	global_store_short v165, v182, s[66:67]
	s_add_u32 s66, s66, 0xb000
	s_addc_u32 s67, s67, 0
	v_mul_f32_e32 v171, 0xbfb8aa3b, v34
	v_mul_f32_e32 v172, 0xbfb8aa3b, v35
	v_mul_f32_e32 v173, 0xbfb8aa3b, v36
	v_mul_f32_e32 v174, 0xbfb8aa3b, v37
	v_exp_f32_e32 v171, v171
	v_exp_f32_e32 v172, v172
	v_exp_f32_e32 v173, v173
	v_exp_f32_e32 v174, v174
	s_nop 0
	v_add_f32_e32 v171, 1.0, v171
	v_add_f32_e32 v172, 1.0, v172
	v_add_f32_e32 v173, 1.0, v173
	v_add_f32_e32 v174, 1.0, v174
	v_rcp_f32_e32 v171, v171
	v_rcp_f32_e32 v172, v172
	v_rcp_f32_e32 v173, v173
	v_rcp_f32_e32 v174, v174
	s_nop 0
	v_mul_f32_e32 v171, v34, v171
	v_mul_f32_e32 v172, v35, v172
	v_mul_f32_e32 v173, v36, v173
	v_mul_f32_e32 v174, v37, v174
	v_mul_f32_e32 v171, v50, v171
	v_mul_f32_e32 v172, v51, v172
	v_mul_f32_e32 v173, v52, v173
	v_mul_f32_e32 v174, v53, v174
	v_cvt_pk_bf16_f32 v179, v171, v171
	v_cvt_pk_bf16_f32 v180, v172, v172
	v_cvt_pk_bf16_f32 v181, v173, v173
	v_cvt_pk_bf16_f32 v182, v174, v174
	global_store_short v162, v179, s[66:67]
	global_store_short v163, v180, s[66:67]
	global_store_short v164, v181, s[66:67]
	global_store_short v165, v182, s[66:67]
	s_add_u32 s66, s66, 0xb000
	s_addc_u32 s67, s67, 0
	v_mul_f32_e32 v171, 0xbfb8aa3b, v38
	v_mul_f32_e32 v172, 0xbfb8aa3b, v39
	v_mul_f32_e32 v173, 0xbfb8aa3b, v40
	v_mul_f32_e32 v174, 0xbfb8aa3b, v41
	v_exp_f32_e32 v171, v171
	v_exp_f32_e32 v172, v172
	v_exp_f32_e32 v173, v173
	v_exp_f32_e32 v174, v174
	s_nop 0
	v_add_f32_e32 v171, 1.0, v171
	v_add_f32_e32 v172, 1.0, v172
	v_add_f32_e32 v173, 1.0, v173
	v_add_f32_e32 v174, 1.0, v174
	v_rcp_f32_e32 v171, v171
	v_rcp_f32_e32 v172, v172
	v_rcp_f32_e32 v173, v173
	v_rcp_f32_e32 v174, v174
	s_nop 0
	v_mul_f32_e32 v171, v38, v171
	v_mul_f32_e32 v172, v39, v172
	v_mul_f32_e32 v173, v40, v173
	v_mul_f32_e32 v174, v41, v174
	v_mul_f32_e32 v171, v54, v171
	v_mul_f32_e32 v172, v55, v172
	v_mul_f32_e32 v173, v56, v173
	v_mul_f32_e32 v174, v57, v174
	v_cvt_pk_bf16_f32 v179, v171, v171
	v_cvt_pk_bf16_f32 v180, v172, v172
	v_cvt_pk_bf16_f32 v181, v173, v173
	v_cvt_pk_bf16_f32 v182, v174, v174
	global_store_short v162, v179, s[66:67]
	global_store_short v163, v180, s[66:67]
	global_store_short v164, v181, s[66:67]
	global_store_short v165, v182, s[66:67]
	s_add_u32 s66, s66, 0xb000
	s_addc_u32 s67, s67, 0
	v_mul_f32_e32 v171, 0xbfb8aa3b, v42
	v_mul_f32_e32 v172, 0xbfb8aa3b, v43
	v_mul_f32_e32 v173, 0xbfb8aa3b, v44
	v_mul_f32_e32 v174, 0xbfb8aa3b, v45
	v_exp_f32_e32 v171, v171
	v_exp_f32_e32 v172, v172
	v_exp_f32_e32 v173, v173
	v_exp_f32_e32 v174, v174
	s_nop 0
	v_add_f32_e32 v171, 1.0, v171
	v_add_f32_e32 v172, 1.0, v172
	v_add_f32_e32 v173, 1.0, v173
	v_add_f32_e32 v174, 1.0, v174
	v_rcp_f32_e32 v171, v171
	v_rcp_f32_e32 v172, v172
	v_rcp_f32_e32 v173, v173
	v_rcp_f32_e32 v174, v174
	s_nop 0
	v_mul_f32_e32 v171, v42, v171
	v_mul_f32_e32 v172, v43, v172
	v_mul_f32_e32 v173, v44, v173
	v_mul_f32_e32 v174, v45, v174
	v_mul_f32_e32 v171, v58, v171
	v_mul_f32_e32 v172, v59, v172
	v_mul_f32_e32 v173, v60, v173
	v_mul_f32_e32 v174, v61, v174
	v_cvt_pk_bf16_f32 v179, v171, v171
	v_cvt_pk_bf16_f32 v180, v172, v172
	v_cvt_pk_bf16_f32 v181, v173, v173
	v_cvt_pk_bf16_f32 v182, v174, v174
	global_store_short v162, v179, s[66:67]
	global_store_short v163, v180, s[66:67]
	global_store_short v164, v181, s[66:67]
	global_store_short v165, v182, s[66:67]
	s_add_u32 s66, s66, 0xb000
	s_addc_u32 s67, s67, 0
	v_mul_f32_e32 v171, 0xbfb8aa3b, v46
	v_mul_f32_e32 v172, 0xbfb8aa3b, v47
	v_mul_f32_e32 v173, 0xbfb8aa3b, v48
	v_mul_f32_e32 v174, 0xbfb8aa3b, v49
	v_exp_f32_e32 v171, v171
	v_exp_f32_e32 v172, v172
	v_exp_f32_e32 v173, v173
	v_exp_f32_e32 v174, v174
	s_nop 0
	v_add_f32_e32 v171, 1.0, v171
	v_add_f32_e32 v172, 1.0, v172
	v_add_f32_e32 v173, 1.0, v173
	v_add_f32_e32 v174, 1.0, v174
	v_rcp_f32_e32 v171, v171
	v_rcp_f32_e32 v172, v172
	v_rcp_f32_e32 v173, v173
	v_rcp_f32_e32 v174, v174
	s_nop 0
	v_mul_f32_e32 v171, v46, v171
	v_mul_f32_e32 v172, v47, v172
	v_mul_f32_e32 v173, v48, v173
	v_mul_f32_e32 v174, v49, v174
	v_mul_f32_e32 v171, v62, v171
	v_mul_f32_e32 v172, v63, v172
	v_mul_f32_e32 v173, v64, v173
	v_mul_f32_e32 v174, v65, v174
	v_cvt_pk_bf16_f32 v179, v171, v171
	v_cvt_pk_bf16_f32 v180, v172, v172
	v_cvt_pk_bf16_f32 v181, v173, v173
	v_cvt_pk_bf16_f32 v182, v174, v174
	global_store_short v162, v179, s[66:67]
	global_store_short v163, v180, s[66:67]
	global_store_short v164, v181, s[66:67]
	global_store_short v165, v182, s[66:67]
	s_sub_u32 s66, s66, 0x4cf80
	s_subb_u32 s67, s67, 0
	v_mul_f32_e32 v171, 0xbfb8aa3b, v66
	v_mul_f32_e32 v172, 0xbfb8aa3b, v67
	v_mul_f32_e32 v173, 0xbfb8aa3b, v68
	v_mul_f32_e32 v174, 0xbfb8aa3b, v69
	v_exp_f32_e32 v171, v171
	v_exp_f32_e32 v172, v172
	v_exp_f32_e32 v173, v173
	v_exp_f32_e32 v174, v174
	s_nop 0
	v_add_f32_e32 v171, 1.0, v171
	v_add_f32_e32 v172, 1.0, v172
	v_add_f32_e32 v173, 1.0, v173
	v_add_f32_e32 v174, 1.0, v174
	v_rcp_f32_e32 v171, v171
	v_rcp_f32_e32 v172, v172
	v_rcp_f32_e32 v173, v173
	v_rcp_f32_e32 v174, v174
	s_nop 0
	v_mul_f32_e32 v171, v66, v171
	v_mul_f32_e32 v172, v67, v172
	v_mul_f32_e32 v173, v68, v173
	v_mul_f32_e32 v174, v69, v174
	v_mul_f32_e32 v171, v82, v171
	v_mul_f32_e32 v172, v83, v172
	v_mul_f32_e32 v173, v84, v173
	v_mul_f32_e32 v174, v85, v174
	v_cvt_pk_bf16_f32 v179, v171, v171
	v_cvt_pk_bf16_f32 v180, v172, v172
	v_cvt_pk_bf16_f32 v181, v173, v173
	v_cvt_pk_bf16_f32 v182, v174, v174
	global_store_short v162, v179, s[66:67]
	global_store_short v163, v180, s[66:67]
	global_store_short v164, v181, s[66:67]
	global_store_short v165, v182, s[66:67]
	s_add_u32 s66, s66, 0xb000
	s_addc_u32 s67, s67, 0
	v_mul_f32_e32 v171, 0xbfb8aa3b, v70
	v_mul_f32_e32 v172, 0xbfb8aa3b, v71
	v_mul_f32_e32 v173, 0xbfb8aa3b, v72
	v_mul_f32_e32 v174, 0xbfb8aa3b, v73
	v_exp_f32_e32 v171, v171
	v_exp_f32_e32 v172, v172
	v_exp_f32_e32 v173, v173
	v_exp_f32_e32 v174, v174
	s_nop 0
	v_add_f32_e32 v171, 1.0, v171
	v_add_f32_e32 v172, 1.0, v172
	v_add_f32_e32 v173, 1.0, v173
	v_add_f32_e32 v174, 1.0, v174
	v_rcp_f32_e32 v171, v171
	v_rcp_f32_e32 v172, v172
	v_rcp_f32_e32 v173, v173
	v_rcp_f32_e32 v174, v174
	s_nop 0
	v_mul_f32_e32 v171, v70, v171
	v_mul_f32_e32 v172, v71, v172
	v_mul_f32_e32 v173, v72, v173
	v_mul_f32_e32 v174, v73, v174
	v_mul_f32_e32 v171, v86, v171
	v_mul_f32_e32 v172, v87, v172
	v_mul_f32_e32 v173, v88, v173
	v_mul_f32_e32 v174, v89, v174
	v_cvt_pk_bf16_f32 v179, v171, v171
	v_cvt_pk_bf16_f32 v180, v172, v172
	v_cvt_pk_bf16_f32 v181, v173, v173
	v_cvt_pk_bf16_f32 v182, v174, v174
	global_store_short v162, v179, s[66:67]
	global_store_short v163, v180, s[66:67]
	global_store_short v164, v181, s[66:67]
	global_store_short v165, v182, s[66:67]
	s_add_u32 s66, s66, 0xb000
	s_addc_u32 s67, s67, 0
	v_mul_f32_e32 v171, 0xbfb8aa3b, v74
	v_mul_f32_e32 v172, 0xbfb8aa3b, v75
	v_mul_f32_e32 v173, 0xbfb8aa3b, v76
	v_mul_f32_e32 v174, 0xbfb8aa3b, v77
	v_exp_f32_e32 v171, v171
	v_exp_f32_e32 v172, v172
	v_exp_f32_e32 v173, v173
	v_exp_f32_e32 v174, v174
	s_nop 0
	v_add_f32_e32 v171, 1.0, v171
	v_add_f32_e32 v172, 1.0, v172
	v_add_f32_e32 v173, 1.0, v173
	v_add_f32_e32 v174, 1.0, v174
	v_rcp_f32_e32 v171, v171
	v_rcp_f32_e32 v172, v172
	v_rcp_f32_e32 v173, v173
	v_rcp_f32_e32 v174, v174
	s_nop 0
	v_mul_f32_e32 v171, v74, v171
	v_mul_f32_e32 v172, v75, v172
	v_mul_f32_e32 v173, v76, v173
	v_mul_f32_e32 v174, v77, v174
	v_mul_f32_e32 v171, v90, v171
	v_mul_f32_e32 v172, v91, v172
	v_mul_f32_e32 v173, v92, v173
	v_mul_f32_e32 v174, v93, v174
	v_cvt_pk_bf16_f32 v179, v171, v171
	v_cvt_pk_bf16_f32 v180, v172, v172
	v_cvt_pk_bf16_f32 v181, v173, v173
	v_cvt_pk_bf16_f32 v182, v174, v174
	global_store_short v162, v179, s[66:67]
	global_store_short v163, v180, s[66:67]
	global_store_short v164, v181, s[66:67]
	global_store_short v165, v182, s[66:67]
	s_add_u32 s66, s66, 0xb000
	s_addc_u32 s67, s67, 0
	v_mul_f32_e32 v171, 0xbfb8aa3b, v78
	v_mul_f32_e32 v172, 0xbfb8aa3b, v79
	v_mul_f32_e32 v173, 0xbfb8aa3b, v80
	v_mul_f32_e32 v174, 0xbfb8aa3b, v81
	v_exp_f32_e32 v171, v171
	v_exp_f32_e32 v172, v172
	v_exp_f32_e32 v173, v173
	v_exp_f32_e32 v174, v174
	s_nop 0
	v_add_f32_e32 v171, 1.0, v171
	v_add_f32_e32 v172, 1.0, v172
	v_add_f32_e32 v173, 1.0, v173
	v_add_f32_e32 v174, 1.0, v174
	v_rcp_f32_e32 v171, v171
	v_rcp_f32_e32 v172, v172
	v_rcp_f32_e32 v173, v173
	v_rcp_f32_e32 v174, v174
	s_nop 0
	v_mul_f32_e32 v171, v78, v171
	v_mul_f32_e32 v172, v79, v172
	v_mul_f32_e32 v173, v80, v173
	v_mul_f32_e32 v174, v81, v174
	v_mul_f32_e32 v171, v94, v171
	v_mul_f32_e32 v172, v95, v172
	v_mul_f32_e32 v173, v96, v173
	v_mul_f32_e32 v174, v97, v174
	v_cvt_pk_bf16_f32 v179, v171, v171
	v_cvt_pk_bf16_f32 v180, v172, v172
	v_cvt_pk_bf16_f32 v181, v173, v173
	v_cvt_pk_bf16_f32 v182, v174, v174
	global_store_short v162, v179, s[66:67]
	global_store_short v163, v180, s[66:67]
	global_store_short v164, v181, s[66:67]
	global_store_short v165, v182, s[66:67]
	s_add_u32 s66, s66, 0xb000
	s_addc_u32 s67, s67, 0
	v_mul_f32_e32 v171, 0xbfb8aa3b, v98
	v_mul_f32_e32 v172, 0xbfb8aa3b, v99
	v_mul_f32_e32 v173, 0xbfb8aa3b, v100
	v_mul_f32_e32 v174, 0xbfb8aa3b, v101
	v_exp_f32_e32 v171, v171
	v_exp_f32_e32 v172, v172
	v_exp_f32_e32 v173, v173
	v_exp_f32_e32 v174, v174
	s_nop 0
	v_add_f32_e32 v171, 1.0, v171
	v_add_f32_e32 v172, 1.0, v172
	v_add_f32_e32 v173, 1.0, v173
	v_add_f32_e32 v174, 1.0, v174
	v_rcp_f32_e32 v171, v171
	v_rcp_f32_e32 v172, v172
	v_rcp_f32_e32 v173, v173
	v_rcp_f32_e32 v174, v174
	s_nop 0
	v_mul_f32_e32 v171, v98, v171
	v_mul_f32_e32 v172, v99, v172
	v_mul_f32_e32 v173, v100, v173
	v_mul_f32_e32 v174, v101, v174
	v_mul_f32_e32 v171, v114, v171
	v_mul_f32_e32 v172, v115, v172
	v_mul_f32_e32 v173, v116, v173
	v_mul_f32_e32 v174, v117, v174
	v_cvt_pk_bf16_f32 v179, v171, v171
	v_cvt_pk_bf16_f32 v180, v172, v172
	v_cvt_pk_bf16_f32 v181, v173, v173
	v_cvt_pk_bf16_f32 v182, v174, v174
	global_store_short v162, v179, s[66:67]
	global_store_short v163, v180, s[66:67]
	global_store_short v164, v181, s[66:67]
	global_store_short v165, v182, s[66:67]
	s_add_u32 s66, s66, 0xb000
	s_addc_u32 s67, s67, 0
	v_mul_f32_e32 v171, 0xbfb8aa3b, v102
	v_mul_f32_e32 v172, 0xbfb8aa3b, v103
	v_mul_f32_e32 v173, 0xbfb8aa3b, v104
	v_mul_f32_e32 v174, 0xbfb8aa3b, v105
	v_exp_f32_e32 v171, v171
	v_exp_f32_e32 v172, v172
	v_exp_f32_e32 v173, v173
	v_exp_f32_e32 v174, v174
	s_nop 0
	v_add_f32_e32 v171, 1.0, v171
	v_add_f32_e32 v172, 1.0, v172
	v_add_f32_e32 v173, 1.0, v173
	v_add_f32_e32 v174, 1.0, v174
	v_rcp_f32_e32 v171, v171
	v_rcp_f32_e32 v172, v172
	v_rcp_f32_e32 v173, v173
	v_rcp_f32_e32 v174, v174
	s_nop 0
	v_mul_f32_e32 v171, v102, v171
	v_mul_f32_e32 v172, v103, v172
	v_mul_f32_e32 v173, v104, v173
	v_mul_f32_e32 v174, v105, v174
	v_mul_f32_e32 v171, v118, v171
	v_mul_f32_e32 v172, v119, v172
	v_mul_f32_e32 v173, v120, v173
	v_mul_f32_e32 v174, v121, v174
	v_cvt_pk_bf16_f32 v179, v171, v171
	v_cvt_pk_bf16_f32 v180, v172, v172
	v_cvt_pk_bf16_f32 v181, v173, v173
	v_cvt_pk_bf16_f32 v182, v174, v174
	global_store_short v162, v179, s[66:67]
	global_store_short v163, v180, s[66:67]
	global_store_short v164, v181, s[66:67]
	global_store_short v165, v182, s[66:67]
	s_add_u32 s66, s66, 0xb000
	s_addc_u32 s67, s67, 0
	v_mul_f32_e32 v171, 0xbfb8aa3b, v106
	v_mul_f32_e32 v172, 0xbfb8aa3b, v107
	v_mul_f32_e32 v173, 0xbfb8aa3b, v108
	v_mul_f32_e32 v174, 0xbfb8aa3b, v109
	v_exp_f32_e32 v171, v171
	v_exp_f32_e32 v172, v172
	v_exp_f32_e32 v173, v173
	v_exp_f32_e32 v174, v174
	s_nop 0
	v_add_f32_e32 v171, 1.0, v171
	v_add_f32_e32 v172, 1.0, v172
	v_add_f32_e32 v173, 1.0, v173
	v_add_f32_e32 v174, 1.0, v174
	v_rcp_f32_e32 v171, v171
	v_rcp_f32_e32 v172, v172
	v_rcp_f32_e32 v173, v173
	v_rcp_f32_e32 v174, v174
	s_nop 0
	v_mul_f32_e32 v171, v106, v171
	v_mul_f32_e32 v172, v107, v172
	v_mul_f32_e32 v173, v108, v173
	v_mul_f32_e32 v174, v109, v174
	v_mul_f32_e32 v171, v122, v171
	v_mul_f32_e32 v172, v123, v172
	v_mul_f32_e32 v173, v124, v173
	v_mul_f32_e32 v174, v125, v174
	v_cvt_pk_bf16_f32 v179, v171, v171
	v_cvt_pk_bf16_f32 v180, v172, v172
	v_cvt_pk_bf16_f32 v181, v173, v173
	v_cvt_pk_bf16_f32 v182, v174, v174
	global_store_short v162, v179, s[66:67]
	global_store_short v163, v180, s[66:67]
	global_store_short v164, v181, s[66:67]
	global_store_short v165, v182, s[66:67]
	s_add_u32 s66, s66, 0xb000
	s_addc_u32 s67, s67, 0
	v_mul_f32_e32 v171, 0xbfb8aa3b, v110
	v_mul_f32_e32 v172, 0xbfb8aa3b, v111
	v_mul_f32_e32 v173, 0xbfb8aa3b, v112
	v_mul_f32_e32 v174, 0xbfb8aa3b, v113
	v_exp_f32_e32 v171, v171
	v_exp_f32_e32 v172, v172
	v_exp_f32_e32 v173, v173
	v_exp_f32_e32 v174, v174
	s_nop 0
	v_add_f32_e32 v171, 1.0, v171
	v_add_f32_e32 v172, 1.0, v172
	v_add_f32_e32 v173, 1.0, v173
	v_add_f32_e32 v174, 1.0, v174
	v_rcp_f32_e32 v171, v171
	v_rcp_f32_e32 v172, v172
	v_rcp_f32_e32 v173, v173
	v_rcp_f32_e32 v174, v174
	s_nop 0
	v_mul_f32_e32 v171, v110, v171
	v_mul_f32_e32 v172, v111, v172
	v_mul_f32_e32 v173, v112, v173
	v_mul_f32_e32 v174, v113, v174
	v_mul_f32_e32 v171, v126, v171
	v_mul_f32_e32 v172, v127, v172
	v_mul_f32_e32 v173, v128, v173
	v_mul_f32_e32 v174, v129, v174
	v_cvt_pk_bf16_f32 v179, v171, v171
	v_cvt_pk_bf16_f32 v180, v172, v172
	v_cvt_pk_bf16_f32 v181, v173, v173
	v_cvt_pk_bf16_f32 v182, v174, v174
	global_store_short v162, v179, s[66:67]
	global_store_short v163, v180, s[66:67]
	global_store_short v164, v181, s[66:67]
	global_store_short v165, v182, s[66:67]
	v_readlane_b32 s62, v246, 14
	s_nop 0
	s_add_i32 s2, s2, s62
	s_branch .Lhw_ffnup_dloop
